# sample-path item: its four initial q/k/v/aq row loads issued together instead of three dependent round trips
# speedup vs baseline: 1.0023x; 1.0023x over previous
.LBB0_292:
	s_and_b32 s18, s8, 7
	v_cvt_f32_ubyte0_e32 v0, s18
	v_sub_f32_e32 v0, 0xc0a00000, v0
	v_exp_f32_e32 v0, v0
	s_mov_b32 s0, 0x800000
	v_lshlrev_b32_e32 v104, 1, v100
	v_sub_f32_e32 v0, 1.0, v0
	v_cmp_gt_f32_e32 vcc, s0, v0
	s_and_b64 s[0:1], vcc, exec
	s_cselect_b32 s0, 32, 0
	v_ldexp_f32 v0, v0, s0
	v_log_f32_e32 v0, v0
	s_mov_b32 s0, 0x3f317217
	s_lshl_b32 s4, s18, 7
	s_barrier
	v_mul_f32_e32 v1, 0x3f317217, v0
	v_fma_f32 v1, v0, s0, -v1
	v_fmac_f32_e32 v1, 0x3377d1cf, v0
	s_mov_b32 s0, 0x7f800000
	v_fmac_f32_e32 v1, 0x3f317217, v0
	v_cmp_lt_f32_e64 s[0:1], |v0|, s0
	s_nop 1
	v_cndmask_b32_e64 v0, v0, v1, s[0:1]
	v_cndmask_b32_e32 v1, 0, v238, vcc
	v_sub_f32_e32 v0, v0, v1
	s_and_b32 s0, s8, -8
	v_mul_f32_e32 v66, 0x3fb8aa3b, v0
	s_waitcnt lgkmcnt(3)
	v_add_u32_e32 v2, s0, v102
	v_mov_b64_e32 v[0:1], s[68:69]
	v_mad_i64_i32 v[0:1], s[2:3], v2, s92, v[0:1]
	v_lshl_add_u64 v[0:1], v[0:1], 0, s[4:5]
	v_lshl_add_u64 v[0:1], v[0:1], 0, v[104:105]
	global_load_ushort v2, v[0:1], off
	s_waitcnt lgkmcnt(2)
	global_load_ushort v3, v[0:1], off offset:1024
	global_load_ushort v4, v[0:1], off offset:2048
	v_add_co_u32_e32 v6, vcc, 0x1000, v0
	s_nop 1
	v_addc_co_u32_e32 v7, vcc, 0, v1, vcc
	global_load_ushort v5, v[6:7], off
	s_waitcnt vmcnt(3)
	v_lshlrev_b32_e32 v2, 16, v2
	s_waitcnt vmcnt(2)
	v_lshlrev_b32_e32 v3, 16, v3
	v_mul_f32_e32 v3, 0x3e000000, v3
	ds_write2st64_b32 v113, v2, v3 offset1:8
	s_waitcnt vmcnt(1)
	v_lshlrev_b32_e32 v2, 16, v4
	s_waitcnt vmcnt(0)
	v_lshlrev_b32_e32 v0, 16, v5
	v_mul_f32_e32 v0, 0x3e000000, v0
	ds_write2st64_b32 v113, v2, v0 offset0:16 offset1:24
	s_waitcnt lgkmcnt(0)
	s_barrier
	s_mov_b64 s[2:3], exec
	v_readlane_b32 s6, v247, 26
	v_readlane_b32 s7, v247, 27
	s_and_b64 s[6:7], s[2:3], s[6:7]
	s_mov_b64 exec, s[6:7]
	s_cbranch_execz .LBB0_298
	v_mov_b32_e32 v0, 0
	s_mov_b64 s[6:7], exec
	v_readlane_b32 s12, v247, 28
	v_readlane_b32 s13, v247, 29
	s_and_b64 s[12:13], s[6:7], s[12:13]
	s_mov_b64 exec, s[12:13]
	s_cbranch_execz .LBB0_297
	v_mov_b32_e32 v0, 0
	s_mov_b32 s1, 0
